# w_in epilogue q/k tiles rewritten: 16 rotary-table loads of a tile issued together (1 round trip instead of 8 load-wait-store rounds), scalar-base stores
# speedup vs baseline: 1.0094x; 1.0094x over previous
; __device__ __forceinline__ unsigned pk2(float lo, float hi) { const f32x2_t v = {lo, hi}; const bf16v2_t b = __builtin_convertvector(v, bf16v2_t); return __builtin_bit_cast(unsigned, b); }
;     __device__ __forceinline__ void operator()(const AccT& acc, const pg8::Unit& u, int wr, int wc, int fr_, int fq_) const {
;     ...
;         if (pn < 4) {
;             const bool isk = pn >= 2;
;             const int jj0 = 16 * (wc & 1) + 4 * fq;
; #pragma unroll
;             for (int ai = 0; ai < 2; ++ai)
; #pragma unroll
;                 for (int m = 0; m < 4; ++m) {
;                     const int rl = rl0 + ai * 128 + m * 16;
;                     const size_t row = (size_t)u.pm * 256 + rl;
;                     f32x4 cs = (f32x4){1.f, 1.f, 1.f, 1.f}, sn = (f32x4){0.f, 0.f, 0.f, 0.f};
;                     if (pt != 0) { const int tpos = (pt - 1) * 256 + rl; cs = *(const f32x4*)(rope + (size_t)tpos * 32 + jj0); sn = *(const f32x4*)(rope + (size_t)SEQ * 32 + (size_t)tpos * 32 + jj0); }
; #pragma unroll
;                     for (int bj = 0; bj < 2; ++bj) {
;                         const int hq = 4 * (pn & 1) + 2 * bj + (wc >> 1);
;                         const f32x4 a1 = acc[ai][bj][m][0], a2 = acc[ai][bj][m][1];
;                         f32x4 o1 = a1 * cs - a2 * sn, o2 = a1 * sn + a2 * cs;
;                         if (isk) { o1 *= 0.125f; o2 *= 0.125f; }
;                         u32x2 p1, p2; p1.x = pk2(o1[0], o1[1]); p1.y = pk2(o1[2], o1[3]); p2.x = pk2(o2[0], o2[1]); p2.y = pk2(o2[2], o2[3]);
;                         bf16_t* dst = (isk ? KN : Q) + row * 512 + hq * 64 + jj0;
;                         *(u32x2*)dst = p1; *(u32x2*)(dst + 32) = p2;
.LBB0_266:
	v_readlane_b32 s2, v254, 38
	v_readlane_b32 s98, v254, 32
	v_readlane_b32 s99, v254, 33
	v_readlane_b32 s15, v254, 36
	s_nop 1
	v_lshl_add_u32 v154, v156, 2, s2
	v_lshlrev_b32_e32 v153, 2, v154
	v_lshl_add_u32 v153, v152, 7, v153
	v_lshlrev_b32_e32 v189, 1, v154
	v_lshl_add_u32 v189, v152, 10, v189
	v_mul_u32_u24_e32 v238, 0x1200, v154
	v_lshl_add_u32 v238, v152, 1, v238
	s_cmp_eq_u32 s71, 0
	s_cbranch_scc1 .Lqk_norope
	s_add_i32 s4, s71, -1
	s_lshl_b32 s4, s4, 15
	s_add_u32 s98, s98, s4
	s_addc_u32 s99, s99, 0
	s_add_u32 s100, s18, s4
	s_addc_u32 s101, s19, 0
	v_add_u32_e32 v155, 0x1000, v153
	v_add_u32_e32 v157, 0x4000, v153
	v_add_u32_e32 v168, 0x5000, v153
	global_load_dwordx4 v[190:193], v153, s[98:99]
	global_load_dwordx4 v[194:197], v153, s[100:101]
	global_load_dwordx4 v[198:201], v153, s[98:99] offset:2048
	global_load_dwordx4 v[202:205], v153, s[100:101] offset:2048
	global_load_dwordx4 v[206:209], v155, s[98:99]
	global_load_dwordx4 v[210:213], v155, s[100:101]
	global_load_dwordx4 v[214:217], v155, s[98:99] offset:2048
	global_load_dwordx4 v[218:221], v155, s[100:101] offset:2048
	global_load_dwordx4 v[222:225], v157, s[98:99]
	global_load_dwordx4 v[226:229], v157, s[100:101]
	global_load_dwordx4 v[230:233], v157, s[98:99] offset:2048
	global_load_dwordx4 v[234:237], v157, s[100:101] offset:2048
	global_load_dwordx4 v[130:133], v168, s[98:99]
	global_load_dwordx4 v[134:137], v168, s[100:101]
	global_load_dwordx4 v[158:161], v168, s[98:99] offset:2048
	global_load_dwordx4 v[162:165], v168, s[100:101] offset:2048
	s_branch .Lqk_go
.Lqk_norope:
	v_mov_b32_e32 v190, 1.0
	v_mov_b32_e32 v191, 1.0
	v_mov_b32_e32 v192, 1.0
	v_mov_b32_e32 v193, 1.0
	v_mov_b32_e32 v194, 0
	v_mov_b32_e32 v195, 0
	v_mov_b32_e32 v196, 0
	v_mov_b32_e32 v197, 0
	v_mov_b32_e32 v198, 1.0
	v_mov_b32_e32 v199, 1.0
	v_mov_b32_e32 v200, 1.0
	v_mov_b32_e32 v201, 1.0
	v_mov_b32_e32 v202, 0
	v_mov_b32_e32 v203, 0
	v_mov_b32_e32 v204, 0
	v_mov_b32_e32 v205, 0
	v_mov_b32_e32 v206, 1.0
	v_mov_b32_e32 v207, 1.0
	v_mov_b32_e32 v208, 1.0
	v_mov_b32_e32 v209, 1.0
	v_mov_b32_e32 v210, 0
	v_mov_b32_e32 v211, 0
	v_mov_b32_e32 v212, 0
	v_mov_b32_e32 v213, 0
	v_mov_b32_e32 v214, 1.0
	v_mov_b32_e32 v215, 1.0
	v_mov_b32_e32 v216, 1.0
	v_mov_b32_e32 v217, 1.0
	v_mov_b32_e32 v218, 0
	v_mov_b32_e32 v219, 0
	v_mov_b32_e32 v220, 0
	v_mov_b32_e32 v221, 0
	v_mov_b32_e32 v222, 1.0
	v_mov_b32_e32 v223, 1.0
	v_mov_b32_e32 v224, 1.0
	v_mov_b32_e32 v225, 1.0
	v_mov_b32_e32 v226, 0
	v_mov_b32_e32 v227, 0
	v_mov_b32_e32 v228, 0
	v_mov_b32_e32 v229, 0
	v_mov_b32_e32 v230, 1.0
	v_mov_b32_e32 v231, 1.0
	v_mov_b32_e32 v232, 1.0
	v_mov_b32_e32 v233, 1.0
	v_mov_b32_e32 v234, 0
	v_mov_b32_e32 v235, 0
	v_mov_b32_e32 v236, 0
	v_mov_b32_e32 v237, 0
	v_mov_b32_e32 v130, 1.0
	v_mov_b32_e32 v131, 1.0
	v_mov_b32_e32 v132, 1.0
	v_mov_b32_e32 v133, 1.0
	v_mov_b32_e32 v134, 0
	v_mov_b32_e32 v135, 0
	v_mov_b32_e32 v136, 0
	v_mov_b32_e32 v137, 0
	v_mov_b32_e32 v158, 1.0
	v_mov_b32_e32 v159, 1.0
	v_mov_b32_e32 v160, 1.0
	v_mov_b32_e32 v161, 1.0
	v_mov_b32_e32 v162, 0
	v_mov_b32_e32 v163, 0
	v_mov_b32_e32 v164, 0
	v_mov_b32_e32 v165, 0
.Lqk_go:
	s_and_b32 s2, s52, 1
	s_lshl_b32 s2, s2, 2
	s_or_b32 s15, s15, s2
	s_cmp_gt_i32 s52, 1
	s_mov_b32 s2, 0xb4c8000
	s_cselect_b32 s2, s2, 0xa2c8000
	s_add_u32 s78, s30, s2
	s_addc_u32 s79, s31, 0
	s_lshl_b32 s2, s14, 18
	s_add_u32 s78, s78, s2
	s_addc_u32 s79, s79, 0
	s_lshl_b32 s2, s15, 7
	s_add_u32 s78, s78, s2
	s_addc_u32 s79, s79, 0
	s_cmp_gt_i32 s52, 1
	s_cbranch_scc1 .Lqk_k
	s_waitcnt vmcnt(0)
	v_pk_mul_f32 v[152:153], v[126:127], v[194:195]
	v_pk_mul_f32 v[154:155], v[128:129], v[196:197]
	v_pk_mul_f32 v[126:127], v[126:127], v[190:191]
	v_pk_mul_f32 v[128:129], v[128:129], v[192:193]
	v_pk_fma_f32 v[152:153], v[122:123], v[190:191], v[152:153] neg_lo:[0,0,1] neg_hi:[0,0,1]
	v_pk_fma_f32 v[154:155], v[124:125], v[192:193], v[154:155] neg_lo:[0,0,1] neg_hi:[0,0,1]
	v_pk_fma_f32 v[126:127], v[122:123], v[194:195], v[126:127]
	v_pk_fma_f32 v[128:129], v[124:125], v[196:197], v[128:129]
	v_cvt_pk_bf16_f32 v122, v152, v153
	v_cvt_pk_bf16_f32 v123, v154, v155
	v_cvt_pk_bf16_f32 v124, v126, v127
	v_cvt_pk_bf16_f32 v125, v128, v129
	global_store_dwordx2 v189, v[122:123], s[78:79]
	global_store_dwordx2 v189, v[124:125], s[78:79] offset:64
	v_pk_mul_f32 v[156:157], v[110:111], v[202:203]
	v_pk_mul_f32 v[168:169], v[112:113], v[204:205]
	v_pk_mul_f32 v[110:111], v[110:111], v[198:199]
	v_pk_mul_f32 v[112:113], v[112:113], v[200:201]
	v_pk_fma_f32 v[156:157], v[106:107], v[198:199], v[156:157] neg_lo:[0,0,1] neg_hi:[0,0,1]
	v_pk_fma_f32 v[168:169], v[108:109], v[200:201], v[168:169] neg_lo:[0,0,1] neg_hi:[0,0,1]
	v_pk_fma_f32 v[110:111], v[106:107], v[202:203], v[110:111]
	v_pk_fma_f32 v[112:113], v[108:109], v[204:205], v[112:113]
	v_cvt_pk_bf16_f32 v106, v156, v157
	v_cvt_pk_bf16_f32 v107, v168, v169
	v_cvt_pk_bf16_f32 v108, v110, v111
	v_cvt_pk_bf16_f32 v109, v112, v113
	v_add_u32_e32 v239, 0x4000, v189
	global_store_dwordx2 v239, v[106:107], s[78:79]
	global_store_dwordx2 v239, v[108:109], s[78:79] offset:64
	v_pk_mul_f32 v[152:153], v[94:95], v[210:211]
	v_pk_mul_f32 v[154:155], v[96:97], v[212:213]
	v_pk_mul_f32 v[94:95], v[94:95], v[206:207]
	v_pk_mul_f32 v[96:97], v[96:97], v[208:209]
	v_pk_fma_f32 v[152:153], v[90:91], v[206:207], v[152:153] neg_lo:[0,0,1] neg_hi:[0,0,1]
	v_pk_fma_f32 v[154:155], v[92:93], v[208:209], v[154:155] neg_lo:[0,0,1] neg_hi:[0,0,1]
	v_pk_fma_f32 v[94:95], v[90:91], v[210:211], v[94:95]
	v_pk_fma_f32 v[96:97], v[92:93], v[212:213], v[96:97]
	v_cvt_pk_bf16_f32 v90, v152, v153
	v_cvt_pk_bf16_f32 v91, v154, v155
	v_cvt_pk_bf16_f32 v92, v94, v95
; __device__ __forceinline__ unsigned pk2(float lo, float hi) { const f32x2_t v = {lo, hi}; const bf16v2_t b = __builtin_convertvector(v, bf16v2_t); return __builtin_bit_cast(unsigned, b); }
;     __device__ __forceinline__ void operator()(const AccT& acc, const pg8::Unit& u, int wr, int wc, int fr_, int fq_) const {
;     ...
;                         const int hq = 4 * (pn & 1) + 2 * bj + (wc >> 1);
;                         const f32x4 a1 = acc[ai][bj][m][0], a2 = acc[ai][bj][m][1];
;                         f32x4 o1 = a1 * cs - a2 * sn, o2 = a1 * sn + a2 * cs;
;                         if (isk) { o1 *= 0.125f; o2 *= 0.125f; }
;                         u32x2 p1, p2; p1.x = pk2(o1[0], o1[1]); p1.y = pk2(o1[2], o1[3]); p2.x = pk2(o2[0], o2[1]); p2.y = pk2(o2[2], o2[3]);
;                         bf16_t* dst = (isk ? KN : Q) + row * 512 + hq * 64 + jj0;
;                         *(u32x2*)dst = p1; *(u32x2*)(dst + 32) = p2;
	v_cvt_pk_bf16_f32 v93, v96, v97
	v_add_u32_e32 v239, 0x8000, v189
	global_store_dwordx2 v239, v[90:91], s[78:79]
	global_store_dwordx2 v239, v[92:93], s[78:79] offset:64
	v_pk_mul_f32 v[156:157], v[78:79], v[218:219]
	v_pk_mul_f32 v[168:169], v[80:81], v[220:221]
	v_pk_mul_f32 v[78:79], v[78:79], v[214:215]
	v_pk_mul_f32 v[80:81], v[80:81], v[216:217]
	v_pk_fma_f32 v[156:157], v[74:75], v[214:215], v[156:157] neg_lo:[0,0,1] neg_hi:[0,0,1]
	v_pk_fma_f32 v[168:169], v[76:77], v[216:217], v[168:169] neg_lo:[0,0,1] neg_hi:[0,0,1]
	v_pk_fma_f32 v[78:79], v[74:75], v[218:219], v[78:79]
	v_pk_fma_f32 v[80:81], v[76:77], v[220:221], v[80:81]
	v_cvt_pk_bf16_f32 v74, v156, v157
	v_cvt_pk_bf16_f32 v75, v168, v169
	v_cvt_pk_bf16_f32 v76, v78, v79
	v_cvt_pk_bf16_f32 v77, v80, v81
	v_add_u32_e32 v239, 0xc000, v189
	global_store_dwordx2 v239, v[74:75], s[78:79]
	global_store_dwordx2 v239, v[76:77], s[78:79] offset:64
	v_pk_mul_f32 v[152:153], v[62:63], v[226:227]
	v_pk_mul_f32 v[154:155], v[64:65], v[228:229]
	v_pk_mul_f32 v[62:63], v[62:63], v[222:223]
	v_pk_mul_f32 v[64:65], v[64:65], v[224:225]
	v_pk_fma_f32 v[152:153], v[58:59], v[222:223], v[152:153] neg_lo:[0,0,1] neg_hi:[0,0,1]
	v_pk_fma_f32 v[154:155], v[60:61], v[224:225], v[154:155] neg_lo:[0,0,1] neg_hi:[0,0,1]
	v_pk_fma_f32 v[62:63], v[58:59], v[226:227], v[62:63]
	v_pk_fma_f32 v[64:65], v[60:61], v[228:229], v[64:65]
	v_cvt_pk_bf16_f32 v58, v152, v153
	v_cvt_pk_bf16_f32 v59, v154, v155
	v_cvt_pk_bf16_f32 v60, v62, v63
	v_cvt_pk_bf16_f32 v61, v64, v65
	v_add_u32_e32 v239, 0x20000, v189
	global_store_dwordx2 v239, v[58:59], s[78:79]
	global_store_dwordx2 v239, v[60:61], s[78:79] offset:64
	v_pk_mul_f32 v[156:157], v[46:47], v[234:235]
	v_pk_mul_f32 v[168:169], v[48:49], v[236:237]
	v_pk_mul_f32 v[46:47], v[46:47], v[230:231]
	v_pk_mul_f32 v[48:49], v[48:49], v[232:233]
	v_pk_fma_f32 v[156:157], v[42:43], v[230:231], v[156:157] neg_lo:[0,0,1] neg_hi:[0,0,1]
	v_pk_fma_f32 v[168:169], v[44:45], v[232:233], v[168:169] neg_lo:[0,0,1] neg_hi:[0,0,1]
	v_pk_fma_f32 v[46:47], v[42:43], v[234:235], v[46:47]
	v_pk_fma_f32 v[48:49], v[44:45], v[236:237], v[48:49]
	v_cvt_pk_bf16_f32 v42, v156, v157
	v_cvt_pk_bf16_f32 v43, v168, v169
	v_cvt_pk_bf16_f32 v44, v46, v47
	v_cvt_pk_bf16_f32 v45, v48, v49
	v_add_u32_e32 v239, 0x24000, v189
	global_store_dwordx2 v239, v[42:43], s[78:79]
	global_store_dwordx2 v239, v[44:45], s[78:79] offset:64
	v_pk_mul_f32 v[152:153], v[30:31], v[134:135]
	v_pk_mul_f32 v[154:155], v[32:33], v[136:137]
	v_pk_mul_f32 v[30:31], v[30:31], v[130:131]
	v_pk_mul_f32 v[32:33], v[32:33], v[132:133]
	v_pk_fma_f32 v[152:153], v[26:27], v[130:131], v[152:153] neg_lo:[0,0,1] neg_hi:[0,0,1]
	v_pk_fma_f32 v[154:155], v[28:29], v[132:133], v[154:155] neg_lo:[0,0,1] neg_hi:[0,0,1]
	v_pk_fma_f32 v[30:31], v[26:27], v[134:135], v[30:31]
	v_pk_fma_f32 v[32:33], v[28:29], v[136:137], v[32:33]
	v_cvt_pk_bf16_f32 v26, v152, v153
	v_cvt_pk_bf16_f32 v27, v154, v155
	v_cvt_pk_bf16_f32 v28, v30, v31
	v_cvt_pk_bf16_f32 v29, v32, v33
	v_add_u32_e32 v239, 0x28000, v189
	global_store_dwordx2 v239, v[26:27], s[78:79]
	global_store_dwordx2 v239, v[28:29], s[78:79] offset:64
	v_pk_mul_f32 v[156:157], v[14:15], v[162:163]
	v_pk_mul_f32 v[168:169], v[16:17], v[164:165]
	v_pk_mul_f32 v[14:15], v[14:15], v[158:159]
	v_pk_mul_f32 v[16:17], v[16:17], v[160:161]
	v_pk_fma_f32 v[156:157], v[10:11], v[158:159], v[156:157] neg_lo:[0,0,1] neg_hi:[0,0,1]
	v_pk_fma_f32 v[168:169], v[12:13], v[160:161], v[168:169] neg_lo:[0,0,1] neg_hi:[0,0,1]
	v_pk_fma_f32 v[14:15], v[10:11], v[162:163], v[14:15]
	v_pk_fma_f32 v[16:17], v[12:13], v[164:165], v[16:17]
	v_cvt_pk_bf16_f32 v10, v156, v157
	v_cvt_pk_bf16_f32 v11, v168, v169
	v_cvt_pk_bf16_f32 v12, v14, v15
	v_cvt_pk_bf16_f32 v13, v16, v17
	v_add_u32_e32 v239, 0x2c000, v189
	global_store_dwordx2 v239, v[10:11], s[78:79]
	global_store_dwordx2 v239, v[12:13], s[78:79] offset:64
	v_pk_mul_f32 v[152:153], v[118:119], v[194:195]
	v_pk_mul_f32 v[154:155], v[120:121], v[196:197]
	v_pk_mul_f32 v[118:119], v[118:119], v[190:191]
	v_pk_mul_f32 v[120:121], v[120:121], v[192:193]
	v_pk_fma_f32 v[152:153], v[114:115], v[190:191], v[152:153] neg_lo:[0,0,1] neg_hi:[0,0,1]
	v_pk_fma_f32 v[154:155], v[116:117], v[192:193], v[154:155] neg_lo:[0,0,1] neg_hi:[0,0,1]
	v_pk_fma_f32 v[118:119], v[114:115], v[194:195], v[118:119]
	v_pk_fma_f32 v[120:121], v[116:117], v[196:197], v[120:121]
	v_cvt_pk_bf16_f32 v114, v152, v153
	v_cvt_pk_bf16_f32 v115, v154, v155
	v_cvt_pk_bf16_f32 v116, v118, v119
	v_cvt_pk_bf16_f32 v117, v120, v121
	global_store_dwordx2 v189, v[114:115], s[78:79] offset:256
	global_store_dwordx2 v189, v[116:117], s[78:79] offset:320
	v_pk_mul_f32 v[156:157], v[102:103], v[202:203]
	v_pk_mul_f32 v[168:169], v[104:105], v[204:205]
	v_pk_mul_f32 v[102:103], v[102:103], v[198:199]
	v_pk_mul_f32 v[104:105], v[104:105], v[200:201]
	v_pk_fma_f32 v[156:157], v[98:99], v[198:199], v[156:157] neg_lo:[0,0,1] neg_hi:[0,0,1]
	v_pk_fma_f32 v[168:169], v[100:101], v[200:201], v[168:169] neg_lo:[0,0,1] neg_hi:[0,0,1]
	v_pk_fma_f32 v[102:103], v[98:99], v[202:203], v[102:103]
	v_pk_fma_f32 v[104:105], v[100:101], v[204:205], v[104:105]
	v_cvt_pk_bf16_f32 v98, v156, v157
	v_cvt_pk_bf16_f32 v99, v168, v169
	v_cvt_pk_bf16_f32 v100, v102, v103
	v_cvt_pk_bf16_f32 v101, v104, v105
	v_add_u32_e32 v239, 0x4000, v189
	global_store_dwordx2 v239, v[98:99], s[78:79] offset:256
	global_store_dwordx2 v239, v[100:101], s[78:79] offset:320
	v_pk_mul_f32 v[152:153], v[86:87], v[210:211]
	v_pk_mul_f32 v[154:155], v[88:89], v[212:213]
	v_pk_mul_f32 v[86:87], v[86:87], v[206:207]
	v_pk_mul_f32 v[88:89], v[88:89], v[208:209]
; __device__ __forceinline__ unsigned pk2(float lo, float hi) { const f32x2_t v = {lo, hi}; const bf16v2_t b = __builtin_convertvector(v, bf16v2_t); return __builtin_bit_cast(unsigned, b); }
;     __device__ __forceinline__ void operator()(const AccT& acc, const pg8::Unit& u, int wr, int wc, int fr_, int fq_) const {
;     ...
;                         const int hq = 4 * (pn & 1) + 2 * bj + (wc >> 1);
;                         const f32x4 a1 = acc[ai][bj][m][0], a2 = acc[ai][bj][m][1];
;                         f32x4 o1 = a1 * cs - a2 * sn, o2 = a1 * sn + a2 * cs;
;                         if (isk) { o1 *= 0.125f; o2 *= 0.125f; }
;                         u32x2 p1, p2; p1.x = pk2(o1[0], o1[1]); p1.y = pk2(o1[2], o1[3]); p2.x = pk2(o2[0], o2[1]); p2.y = pk2(o2[2], o2[3]);
;                         bf16_t* dst = (isk ? KN : Q) + row * 512 + hq * 64 + jj0;
;                         *(u32x2*)dst = p1; *(u32x2*)(dst + 32) = p2;
	v_pk_fma_f32 v[152:153], v[82:83], v[206:207], v[152:153] neg_lo:[0,0,1] neg_hi:[0,0,1]
	v_pk_fma_f32 v[154:155], v[84:85], v[208:209], v[154:155] neg_lo:[0,0,1] neg_hi:[0,0,1]
	v_pk_fma_f32 v[86:87], v[82:83], v[210:211], v[86:87]
	v_pk_fma_f32 v[88:89], v[84:85], v[212:213], v[88:89]
	v_cvt_pk_bf16_f32 v82, v152, v153
	v_cvt_pk_bf16_f32 v83, v154, v155
	v_cvt_pk_bf16_f32 v84, v86, v87
	v_cvt_pk_bf16_f32 v85, v88, v89
	v_add_u32_e32 v239, 0x8000, v189
	global_store_dwordx2 v239, v[82:83], s[78:79] offset:256
	global_store_dwordx2 v239, v[84:85], s[78:79] offset:320
	v_pk_mul_f32 v[156:157], v[70:71], v[218:219]
	v_pk_mul_f32 v[168:169], v[72:73], v[220:221]
	v_pk_mul_f32 v[70:71], v[70:71], v[214:215]
	v_pk_mul_f32 v[72:73], v[72:73], v[216:217]
	v_pk_fma_f32 v[156:157], v[66:67], v[214:215], v[156:157] neg_lo:[0,0,1] neg_hi:[0,0,1]
	v_pk_fma_f32 v[168:169], v[68:69], v[216:217], v[168:169] neg_lo:[0,0,1] neg_hi:[0,0,1]
	v_pk_fma_f32 v[70:71], v[66:67], v[218:219], v[70:71]
	v_pk_fma_f32 v[72:73], v[68:69], v[220:221], v[72:73]
	v_cvt_pk_bf16_f32 v66, v156, v157
	v_cvt_pk_bf16_f32 v67, v168, v169
	v_cvt_pk_bf16_f32 v68, v70, v71
	v_cvt_pk_bf16_f32 v69, v72, v73
	v_add_u32_e32 v239, 0xc000, v189
	global_store_dwordx2 v239, v[66:67], s[78:79] offset:256
	global_store_dwordx2 v239, v[68:69], s[78:79] offset:320
	v_pk_mul_f32 v[152:153], v[54:55], v[226:227]
	v_pk_mul_f32 v[154:155], v[56:57], v[228:229]
	v_pk_mul_f32 v[54:55], v[54:55], v[222:223]
	v_pk_mul_f32 v[56:57], v[56:57], v[224:225]
	v_pk_fma_f32 v[152:153], v[50:51], v[222:223], v[152:153] neg_lo:[0,0,1] neg_hi:[0,0,1]
	v_pk_fma_f32 v[154:155], v[52:53], v[224:225], v[154:155] neg_lo:[0,0,1] neg_hi:[0,0,1]
	v_pk_fma_f32 v[54:55], v[50:51], v[226:227], v[54:55]
	v_pk_fma_f32 v[56:57], v[52:53], v[228:229], v[56:57]
	v_cvt_pk_bf16_f32 v50, v152, v153
	v_cvt_pk_bf16_f32 v51, v154, v155
	v_cvt_pk_bf16_f32 v52, v54, v55
	v_cvt_pk_bf16_f32 v53, v56, v57
	v_add_u32_e32 v239, 0x20000, v189
	global_store_dwordx2 v239, v[50:51], s[78:79] offset:256
	global_store_dwordx2 v239, v[52:53], s[78:79] offset:320
	v_pk_mul_f32 v[156:157], v[38:39], v[234:235]
	v_pk_mul_f32 v[168:169], v[40:41], v[236:237]
	v_pk_mul_f32 v[38:39], v[38:39], v[230:231]
	v_pk_mul_f32 v[40:41], v[40:41], v[232:233]
	v_pk_fma_f32 v[156:157], v[34:35], v[230:231], v[156:157] neg_lo:[0,0,1] neg_hi:[0,0,1]
	v_pk_fma_f32 v[168:169], v[36:37], v[232:233], v[168:169] neg_lo:[0,0,1] neg_hi:[0,0,1]
	v_pk_fma_f32 v[38:39], v[34:35], v[234:235], v[38:39]
	v_pk_fma_f32 v[40:41], v[36:37], v[236:237], v[40:41]
	v_cvt_pk_bf16_f32 v34, v156, v157
	v_cvt_pk_bf16_f32 v35, v168, v169
	v_cvt_pk_bf16_f32 v36, v38, v39
	v_cvt_pk_bf16_f32 v37, v40, v41
	v_add_u32_e32 v239, 0x24000, v189
	global_store_dwordx2 v239, v[34:35], s[78:79] offset:256
	global_store_dwordx2 v239, v[36:37], s[78:79] offset:320
	v_pk_mul_f32 v[152:153], v[22:23], v[134:135]
	v_pk_mul_f32 v[154:155], v[24:25], v[136:137]
	v_pk_mul_f32 v[22:23], v[22:23], v[130:131]
	v_pk_mul_f32 v[24:25], v[24:25], v[132:133]
	v_pk_fma_f32 v[152:153], v[18:19], v[130:131], v[152:153] neg_lo:[0,0,1] neg_hi:[0,0,1]
	v_pk_fma_f32 v[154:155], v[20:21], v[132:133], v[154:155] neg_lo:[0,0,1] neg_hi:[0,0,1]
	v_pk_fma_f32 v[22:23], v[18:19], v[134:135], v[22:23]
	v_pk_fma_f32 v[24:25], v[20:21], v[136:137], v[24:25]
	v_cvt_pk_bf16_f32 v18, v152, v153
	v_cvt_pk_bf16_f32 v19, v154, v155
	v_cvt_pk_bf16_f32 v20, v22, v23
	v_cvt_pk_bf16_f32 v21, v24, v25
	v_add_u32_e32 v239, 0x28000, v189
	global_store_dwordx2 v239, v[18:19], s[78:79] offset:256
	global_store_dwordx2 v239, v[20:21], s[78:79] offset:320
	v_pk_mul_f32 v[156:157], v[2:3], v[162:163]
	v_pk_mul_f32 v[168:169], v[4:5], v[164:165]
	v_pk_mul_f32 v[2:3], v[2:3], v[158:159]
	v_pk_mul_f32 v[4:5], v[4:5], v[160:161]
	v_pk_fma_f32 v[156:157], v[6:7], v[158:159], v[156:157] neg_lo:[0,0,1] neg_hi:[0,0,1]
	v_pk_fma_f32 v[168:169], v[8:9], v[160:161], v[168:169] neg_lo:[0,0,1] neg_hi:[0,0,1]
	v_pk_fma_f32 v[2:3], v[6:7], v[162:163], v[2:3]
	v_pk_fma_f32 v[4:5], v[8:9], v[164:165], v[4:5]
	v_cvt_pk_bf16_f32 v6, v156, v157
	v_cvt_pk_bf16_f32 v7, v168, v169
	v_cvt_pk_bf16_f32 v8, v2, v3
	v_cvt_pk_bf16_f32 v9, v4, v5
	v_add_u32_e32 v239, 0x2c000, v189
	global_store_dwordx2 v239, v[6:7], s[78:79] offset:256
	global_store_dwordx2 v239, v[8:9], s[78:79] offset:320
	s_branch .LBB0_323
; __device__ __forceinline__ unsigned pk2(float lo, float hi) { const f32x2_t v = {lo, hi}; const bf16v2_t b = __builtin_convertvector(v, bf16v2_t); return __builtin_bit_cast(unsigned, b); }
;     __device__ __forceinline__ void operator()(const AccT& acc, const pg8::Unit& u, int wr, int wc, int fr_, int fq_) const {
;     ...
;                         const int hq = 4 * (pn & 1) + 2 * bj + (wc >> 1);
;                         const f32x4 a1 = acc[ai][bj][m][0], a2 = acc[ai][bj][m][1];
;                         f32x4 o1 = a1 * cs - a2 * sn, o2 = a1 * sn + a2 * cs;
;                         if (isk) { o1 *= 0.125f; o2 *= 0.125f; }
;                         u32x2 p1, p2; p1.x = pk2(o1[0], o1[1]); p1.y = pk2(o1[2], o1[3]); p2.x = pk2(o2[0], o2[1]); p2.y = pk2(o2[2], o2[3]);
;                         bf16_t* dst = (isk ? KN : Q) + row * 512 + hq * 64 + jj0;
;                         *(u32x2*)dst = p1; *(u32x2*)(dst + 32) = p2;
;                         if (isk) {
;                             bf16_t* kt = KT + ((size_t)(b * NH + hq) * DK + jj0) * TB + pt * 256 + rl;
;                             kt[0] = (bf16_t)(p1.x & 0xffffu); kt[(size_t)TB] = (bf16_t)(p1.x >> 16); kt[(size_t)2 * TB] = (bf16_t)(p1.y & 0xffffu); kt[(size_t)3 * TB] = (bf16_t)(p1.y >> 16);
;                             bf16_t* kt2 = kt + (size_t)32 * TB;
;                             kt2[0] = (bf16_t)(p2.x & 0xffffu); kt2[(size_t)TB] = (bf16_t)(p2.x >> 16); kt2[(size_t)2 * TB] = (bf16_t)(p2.y & 0xffffu); kt2[(size_t)3 * TB] = (bf16_t)(p2.y >> 16);
;                         }
.Lqk_k:
	s_lshl_b32 s2, s69, 3
	s_add_i32 s2, s2, s15
	s_mul_i32 s2, s2, 0x48000
	s_lshl_b32 s75, s71, 9
	s_add_i32 s2, s2, s75
	s_addk_i32 s2, 0x900
	s_add_u32 s4, s56, s2
	s_addc_u32 s5, s57, 0
	s_waitcnt vmcnt(0)
	s_add_u32 s8, s4, 0x2400
	s_addc_u32 s9, s5, 0
	s_add_u32 s10, s4, 0x24000
	s_addc_u32 s11, s5, 0
	s_add_u32 s12, s10, 0x2400
	s_addc_u32 s13, s11, 0
	v_pk_mul_f32 v[152:153], v[126:127], v[194:195]
	v_pk_mul_f32 v[154:155], v[128:129], v[196:197]
	v_pk_mul_f32 v[126:127], v[126:127], v[190:191]
	v_pk_mul_f32 v[128:129], v[128:129], v[192:193]
	v_pk_fma_f32 v[152:153], v[122:123], v[190:191], v[152:153] neg_lo:[0,0,1] neg_hi:[0,0,1]
	v_pk_fma_f32 v[154:155], v[124:125], v[192:193], v[154:155] neg_lo:[0,0,1] neg_hi:[0,0,1]
	v_pk_fma_f32 v[126:127], v[122:123], v[194:195], v[126:127]
	v_pk_fma_f32 v[128:129], v[124:125], v[196:197], v[128:129]
	v_pk_mul_f32 v[152:153], v[152:153], s[84:85] op_sel_hi:[1,0]
	v_pk_mul_f32 v[154:155], v[154:155], s[84:85] op_sel_hi:[1,0]
	v_pk_mul_f32 v[126:127], v[126:127], s[84:85] op_sel_hi:[1,0]
	v_pk_mul_f32 v[128:129], v[128:129], s[84:85] op_sel_hi:[1,0]
	v_cvt_pk_bf16_f32 v122, v152, v153
	v_cvt_pk_bf16_f32 v123, v154, v155
	v_cvt_pk_bf16_f32 v124, v126, v127
	v_cvt_pk_bf16_f32 v125, v128, v129
	global_store_dwordx2 v189, v[122:123], s[78:79]
	global_store_dwordx2 v189, v[124:125], s[78:79] offset:64
	global_store_short v238, v122, s[4:5] offset:-2304
	global_store_short_d16_hi v238, v122, s[4:5] offset:2304
	global_store_short v238, v123, s[8:9] offset:-2304
	global_store_short_d16_hi v238, v123, s[8:9] offset:2304
	global_store_short v238, v124, s[10:11] offset:-2304
	global_store_short_d16_hi v238, v124, s[10:11] offset:2304
	global_store_short v238, v125, s[12:13] offset:-2304
	global_store_short_d16_hi v238, v125, s[12:13] offset:2304
	v_pk_mul_f32 v[156:157], v[110:111], v[202:203]
	v_pk_mul_f32 v[168:169], v[112:113], v[204:205]
	v_pk_mul_f32 v[110:111], v[110:111], v[198:199]
	v_pk_mul_f32 v[112:113], v[112:113], v[200:201]
	v_pk_fma_f32 v[156:157], v[106:107], v[198:199], v[156:157] neg_lo:[0,0,1] neg_hi:[0,0,1]
	v_pk_fma_f32 v[168:169], v[108:109], v[200:201], v[168:169] neg_lo:[0,0,1] neg_hi:[0,0,1]
	v_pk_fma_f32 v[110:111], v[106:107], v[202:203], v[110:111]
	v_pk_fma_f32 v[112:113], v[108:109], v[204:205], v[112:113]
	v_pk_mul_f32 v[156:157], v[156:157], s[84:85] op_sel_hi:[1,0]
	v_pk_mul_f32 v[168:169], v[168:169], s[84:85] op_sel_hi:[1,0]
	v_pk_mul_f32 v[110:111], v[110:111], s[84:85] op_sel_hi:[1,0]
	v_pk_mul_f32 v[112:113], v[112:113], s[84:85] op_sel_hi:[1,0]
	v_cvt_pk_bf16_f32 v106, v156, v157
	v_cvt_pk_bf16_f32 v107, v168, v169
	v_cvt_pk_bf16_f32 v108, v110, v111
	v_cvt_pk_bf16_f32 v109, v112, v113
	v_add_u32_e32 v239, 0x4000, v189
	global_store_dwordx2 v239, v[106:107], s[78:79]
	global_store_dwordx2 v239, v[108:109], s[78:79] offset:64
	global_store_short v238, v106, s[4:5] offset:-2272
	global_store_short_d16_hi v238, v106, s[4:5] offset:2336
	global_store_short v238, v107, s[8:9] offset:-2272
	global_store_short_d16_hi v238, v107, s[8:9] offset:2336
	global_store_short v238, v108, s[10:11] offset:-2272
	global_store_short_d16_hi v238, v108, s[10:11] offset:2336
	global_store_short v238, v109, s[12:13] offset:-2272
	global_store_short_d16_hi v238, v109, s[12:13] offset:2336
	v_pk_mul_f32 v[152:153], v[94:95], v[210:211]
	v_pk_mul_f32 v[154:155], v[96:97], v[212:213]
	v_pk_mul_f32 v[94:95], v[94:95], v[206:207]
	v_pk_mul_f32 v[96:97], v[96:97], v[208:209]
	v_pk_fma_f32 v[152:153], v[90:91], v[206:207], v[152:153] neg_lo:[0,0,1] neg_hi:[0,0,1]
	v_pk_fma_f32 v[154:155], v[92:93], v[208:209], v[154:155] neg_lo:[0,0,1] neg_hi:[0,0,1]
	v_pk_fma_f32 v[94:95], v[90:91], v[210:211], v[94:95]
	v_pk_fma_f32 v[96:97], v[92:93], v[212:213], v[96:97]
	v_pk_mul_f32 v[152:153], v[152:153], s[84:85] op_sel_hi:[1,0]
	v_pk_mul_f32 v[154:155], v[154:155], s[84:85] op_sel_hi:[1,0]
	v_pk_mul_f32 v[94:95], v[94:95], s[84:85] op_sel_hi:[1,0]
	v_pk_mul_f32 v[96:97], v[96:97], s[84:85] op_sel_hi:[1,0]
	v_cvt_pk_bf16_f32 v90, v152, v153
	v_cvt_pk_bf16_f32 v91, v154, v155
	v_cvt_pk_bf16_f32 v92, v94, v95
	v_cvt_pk_bf16_f32 v93, v96, v97
	v_add_u32_e32 v239, 0x8000, v189
	global_store_dwordx2 v239, v[90:91], s[78:79]
	global_store_dwordx2 v239, v[92:93], s[78:79] offset:64
	global_store_short v238, v90, s[4:5] offset:-2240
	global_store_short_d16_hi v238, v90, s[4:5] offset:2368
	global_store_short v238, v91, s[8:9] offset:-2240
	global_store_short_d16_hi v238, v91, s[8:9] offset:2368
	global_store_short v238, v92, s[10:11] offset:-2240
	global_store_short_d16_hi v238, v92, s[10:11] offset:2368
	global_store_short v238, v93, s[12:13] offset:-2240
	global_store_short_d16_hi v238, v93, s[12:13] offset:2368
	v_pk_mul_f32 v[156:157], v[78:79], v[218:219]
	v_pk_mul_f32 v[168:169], v[80:81], v[220:221]
	v_pk_mul_f32 v[78:79], v[78:79], v[214:215]
	v_pk_mul_f32 v[80:81], v[80:81], v[216:217]
	v_pk_fma_f32 v[156:157], v[74:75], v[214:215], v[156:157] neg_lo:[0,0,1] neg_hi:[0,0,1]
	v_pk_fma_f32 v[168:169], v[76:77], v[216:217], v[168:169] neg_lo:[0,0,1] neg_hi:[0,0,1]
	v_pk_fma_f32 v[78:79], v[74:75], v[218:219], v[78:79]
	v_pk_fma_f32 v[80:81], v[76:77], v[220:221], v[80:81]
	v_pk_mul_f32 v[156:157], v[156:157], s[84:85] op_sel_hi:[1,0]
	v_pk_mul_f32 v[168:169], v[168:169], s[84:85] op_sel_hi:[1,0]
	v_pk_mul_f32 v[78:79], v[78:79], s[84:85] op_sel_hi:[1,0]
	v_pk_mul_f32 v[80:81], v[80:81], s[84:85] op_sel_hi:[1,0]
	v_cvt_pk_bf16_f32 v74, v156, v157
	v_cvt_pk_bf16_f32 v75, v168, v169
	v_cvt_pk_bf16_f32 v76, v78, v79
	v_cvt_pk_bf16_f32 v77, v80, v81
	v_add_u32_e32 v239, 0xc000, v189
; __device__ __forceinline__ unsigned pk2(float lo, float hi) { const f32x2_t v = {lo, hi}; const bf16v2_t b = __builtin_convertvector(v, bf16v2_t); return __builtin_bit_cast(unsigned, b); }
;     __device__ __forceinline__ void operator()(const AccT& acc, const pg8::Unit& u, int wr, int wc, int fr_, int fq_) const {
;     ...
;                         const int hq = 4 * (pn & 1) + 2 * bj + (wc >> 1);
;                         const f32x4 a1 = acc[ai][bj][m][0], a2 = acc[ai][bj][m][1];
;                         f32x4 o1 = a1 * cs - a2 * sn, o2 = a1 * sn + a2 * cs;
;                         if (isk) { o1 *= 0.125f; o2 *= 0.125f; }
;                         u32x2 p1, p2; p1.x = pk2(o1[0], o1[1]); p1.y = pk2(o1[2], o1[3]); p2.x = pk2(o2[0], o2[1]); p2.y = pk2(o2[2], o2[3]);
;                         bf16_t* dst = (isk ? KN : Q) + row * 512 + hq * 64 + jj0;
;                         *(u32x2*)dst = p1; *(u32x2*)(dst + 32) = p2;
;                         if (isk) {
;                             bf16_t* kt = KT + ((size_t)(b * NH + hq) * DK + jj0) * TB + pt * 256 + rl;
;                             kt[0] = (bf16_t)(p1.x & 0xffffu); kt[(size_t)TB] = (bf16_t)(p1.x >> 16); kt[(size_t)2 * TB] = (bf16_t)(p1.y & 0xffffu); kt[(size_t)3 * TB] = (bf16_t)(p1.y >> 16);
;                             bf16_t* kt2 = kt + (size_t)32 * TB;
;                             kt2[0] = (bf16_t)(p2.x & 0xffffu); kt2[(size_t)TB] = (bf16_t)(p2.x >> 16); kt2[(size_t)2 * TB] = (bf16_t)(p2.y & 0xffffu); kt2[(size_t)3 * TB] = (bf16_t)(p2.y >> 16);
;                         }
	global_store_dwordx2 v239, v[74:75], s[78:79]
	global_store_dwordx2 v239, v[76:77], s[78:79] offset:64
	global_store_short v238, v74, s[4:5] offset:-2208
	global_store_short_d16_hi v238, v74, s[4:5] offset:2400
	global_store_short v238, v75, s[8:9] offset:-2208
	global_store_short_d16_hi v238, v75, s[8:9] offset:2400
	global_store_short v238, v76, s[10:11] offset:-2208
	global_store_short_d16_hi v238, v76, s[10:11] offset:2400
	global_store_short v238, v77, s[12:13] offset:-2208
	global_store_short_d16_hi v238, v77, s[12:13] offset:2400
	v_pk_mul_f32 v[152:153], v[62:63], v[226:227]
	v_pk_mul_f32 v[154:155], v[64:65], v[228:229]
	v_pk_mul_f32 v[62:63], v[62:63], v[222:223]
	v_pk_mul_f32 v[64:65], v[64:65], v[224:225]
	v_pk_fma_f32 v[152:153], v[58:59], v[222:223], v[152:153] neg_lo:[0,0,1] neg_hi:[0,0,1]
	v_pk_fma_f32 v[154:155], v[60:61], v[224:225], v[154:155] neg_lo:[0,0,1] neg_hi:[0,0,1]
	v_pk_fma_f32 v[62:63], v[58:59], v[226:227], v[62:63]
	v_pk_fma_f32 v[64:65], v[60:61], v[228:229], v[64:65]
	v_pk_mul_f32 v[152:153], v[152:153], s[84:85] op_sel_hi:[1,0]
	v_pk_mul_f32 v[154:155], v[154:155], s[84:85] op_sel_hi:[1,0]
	v_pk_mul_f32 v[62:63], v[62:63], s[84:85] op_sel_hi:[1,0]
	v_pk_mul_f32 v[64:65], v[64:65], s[84:85] op_sel_hi:[1,0]
	v_cvt_pk_bf16_f32 v58, v152, v153
	v_cvt_pk_bf16_f32 v59, v154, v155
	v_cvt_pk_bf16_f32 v60, v62, v63
	v_cvt_pk_bf16_f32 v61, v64, v65
	v_add_u32_e32 v239, 0x20000, v189
	global_store_dwordx2 v239, v[58:59], s[78:79]
	global_store_dwordx2 v239, v[60:61], s[78:79] offset:64
	global_store_short v238, v58, s[4:5] offset:-2048
	global_store_short_d16_hi v238, v58, s[4:5] offset:2560
	global_store_short v238, v59, s[8:9] offset:-2048
	global_store_short_d16_hi v238, v59, s[8:9] offset:2560
	global_store_short v238, v60, s[10:11] offset:-2048
	global_store_short_d16_hi v238, v60, s[10:11] offset:2560
	global_store_short v238, v61, s[12:13] offset:-2048
	global_store_short_d16_hi v238, v61, s[12:13] offset:2560
	v_pk_mul_f32 v[156:157], v[46:47], v[234:235]
	v_pk_mul_f32 v[168:169], v[48:49], v[236:237]
	v_pk_mul_f32 v[46:47], v[46:47], v[230:231]
	v_pk_mul_f32 v[48:49], v[48:49], v[232:233]
	v_pk_fma_f32 v[156:157], v[42:43], v[230:231], v[156:157] neg_lo:[0,0,1] neg_hi:[0,0,1]
	v_pk_fma_f32 v[168:169], v[44:45], v[232:233], v[168:169] neg_lo:[0,0,1] neg_hi:[0,0,1]
	v_pk_fma_f32 v[46:47], v[42:43], v[234:235], v[46:47]
	v_pk_fma_f32 v[48:49], v[44:45], v[236:237], v[48:49]
	v_pk_mul_f32 v[156:157], v[156:157], s[84:85] op_sel_hi:[1,0]
	v_pk_mul_f32 v[168:169], v[168:169], s[84:85] op_sel_hi:[1,0]
	v_pk_mul_f32 v[46:47], v[46:47], s[84:85] op_sel_hi:[1,0]
	v_pk_mul_f32 v[48:49], v[48:49], s[84:85] op_sel_hi:[1,0]
	v_cvt_pk_bf16_f32 v42, v156, v157
	v_cvt_pk_bf16_f32 v43, v168, v169
	v_cvt_pk_bf16_f32 v44, v46, v47
	v_cvt_pk_bf16_f32 v45, v48, v49
	v_add_u32_e32 v239, 0x24000, v189
	global_store_dwordx2 v239, v[42:43], s[78:79]
	global_store_dwordx2 v239, v[44:45], s[78:79] offset:64
	global_store_short v238, v42, s[4:5] offset:-2016
	global_store_short_d16_hi v238, v42, s[4:5] offset:2592
	global_store_short v238, v43, s[8:9] offset:-2016
	global_store_short_d16_hi v238, v43, s[8:9] offset:2592
	global_store_short v238, v44, s[10:11] offset:-2016
	global_store_short_d16_hi v238, v44, s[10:11] offset:2592
	global_store_short v238, v45, s[12:13] offset:-2016
	global_store_short_d16_hi v238, v45, s[12:13] offset:2592
	v_pk_mul_f32 v[152:153], v[30:31], v[134:135]
	v_pk_mul_f32 v[154:155], v[32:33], v[136:137]
	v_pk_mul_f32 v[30:31], v[30:31], v[130:131]
	v_pk_mul_f32 v[32:33], v[32:33], v[132:133]
	v_pk_fma_f32 v[152:153], v[26:27], v[130:131], v[152:153] neg_lo:[0,0,1] neg_hi:[0,0,1]
	v_pk_fma_f32 v[154:155], v[28:29], v[132:133], v[154:155] neg_lo:[0,0,1] neg_hi:[0,0,1]
	v_pk_fma_f32 v[30:31], v[26:27], v[134:135], v[30:31]
	v_pk_fma_f32 v[32:33], v[28:29], v[136:137], v[32:33]
	v_pk_mul_f32 v[152:153], v[152:153], s[84:85] op_sel_hi:[1,0]
	v_pk_mul_f32 v[154:155], v[154:155], s[84:85] op_sel_hi:[1,0]
	v_pk_mul_f32 v[30:31], v[30:31], s[84:85] op_sel_hi:[1,0]
	v_pk_mul_f32 v[32:33], v[32:33], s[84:85] op_sel_hi:[1,0]
	v_cvt_pk_bf16_f32 v26, v152, v153
	v_cvt_pk_bf16_f32 v27, v154, v155
	v_cvt_pk_bf16_f32 v28, v30, v31
	v_cvt_pk_bf16_f32 v29, v32, v33
	v_add_u32_e32 v239, 0x28000, v189
	global_store_dwordx2 v239, v[26:27], s[78:79]
	global_store_dwordx2 v239, v[28:29], s[78:79] offset:64
	global_store_short v238, v26, s[4:5] offset:-1984
	global_store_short_d16_hi v238, v26, s[4:5] offset:2624
	global_store_short v238, v27, s[8:9] offset:-1984
	global_store_short_d16_hi v238, v27, s[8:9] offset:2624
	global_store_short v238, v28, s[10:11] offset:-1984
	global_store_short_d16_hi v238, v28, s[10:11] offset:2624
	global_store_short v238, v29, s[12:13] offset:-1984
	global_store_short_d16_hi v238, v29, s[12:13] offset:2624
	v_pk_mul_f32 v[156:157], v[14:15], v[162:163]
	v_pk_mul_f32 v[168:169], v[16:17], v[164:165]
	v_pk_mul_f32 v[14:15], v[14:15], v[158:159]
	v_pk_mul_f32 v[16:17], v[16:17], v[160:161]
	v_pk_fma_f32 v[156:157], v[10:11], v[158:159], v[156:157] neg_lo:[0,0,1] neg_hi:[0,0,1]
	v_pk_fma_f32 v[168:169], v[12:13], v[160:161], v[168:169] neg_lo:[0,0,1] neg_hi:[0,0,1]
	v_pk_fma_f32 v[14:15], v[10:11], v[162:163], v[14:15]
	v_pk_fma_f32 v[16:17], v[12:13], v[164:165], v[16:17]
	v_pk_mul_f32 v[156:157], v[156:157], s[84:85] op_sel_hi:[1,0]
	v_pk_mul_f32 v[168:169], v[168:169], s[84:85] op_sel_hi:[1,0]
	v_pk_mul_f32 v[14:15], v[14:15], s[84:85] op_sel_hi:[1,0]
	v_pk_mul_f32 v[16:17], v[16:17], s[84:85] op_sel_hi:[1,0]
	v_cvt_pk_bf16_f32 v10, v156, v157
	v_cvt_pk_bf16_f32 v11, v168, v169
	v_cvt_pk_bf16_f32 v12, v14, v15
; __device__ __forceinline__ unsigned pk2(float lo, float hi) { const f32x2_t v = {lo, hi}; const bf16v2_t b = __builtin_convertvector(v, bf16v2_t); return __builtin_bit_cast(unsigned, b); }
;     __device__ __forceinline__ void operator()(const AccT& acc, const pg8::Unit& u, int wr, int wc, int fr_, int fq_) const {
;     ...
;                         const int hq = 4 * (pn & 1) + 2 * bj + (wc >> 1);
;                         const f32x4 a1 = acc[ai][bj][m][0], a2 = acc[ai][bj][m][1];
;                         f32x4 o1 = a1 * cs - a2 * sn, o2 = a1 * sn + a2 * cs;
;                         if (isk) { o1 *= 0.125f; o2 *= 0.125f; }
;                         u32x2 p1, p2; p1.x = pk2(o1[0], o1[1]); p1.y = pk2(o1[2], o1[3]); p2.x = pk2(o2[0], o2[1]); p2.y = pk2(o2[2], o2[3]);
;                         bf16_t* dst = (isk ? KN : Q) + row * 512 + hq * 64 + jj0;
;                         *(u32x2*)dst = p1; *(u32x2*)(dst + 32) = p2;
;                         if (isk) {
;                             bf16_t* kt = KT + ((size_t)(b * NH + hq) * DK + jj0) * TB + pt * 256 + rl;
;                             kt[0] = (bf16_t)(p1.x & 0xffffu); kt[(size_t)TB] = (bf16_t)(p1.x >> 16); kt[(size_t)2 * TB] = (bf16_t)(p1.y & 0xffffu); kt[(size_t)3 * TB] = (bf16_t)(p1.y >> 16);
;                             bf16_t* kt2 = kt + (size_t)32 * TB;
;                             kt2[0] = (bf16_t)(p2.x & 0xffffu); kt2[(size_t)TB] = (bf16_t)(p2.x >> 16); kt2[(size_t)2 * TB] = (bf16_t)(p2.y & 0xffffu); kt2[(size_t)3 * TB] = (bf16_t)(p2.y >> 16);
;                         }
	v_cvt_pk_bf16_f32 v13, v16, v17
	v_add_u32_e32 v239, 0x2c000, v189
	global_store_dwordx2 v239, v[10:11], s[78:79]
	global_store_dwordx2 v239, v[12:13], s[78:79] offset:64
	global_store_short v238, v10, s[4:5] offset:-1952
	global_store_short_d16_hi v238, v10, s[4:5] offset:2656
	global_store_short v238, v11, s[8:9] offset:-1952
	global_store_short_d16_hi v238, v11, s[8:9] offset:2656
	global_store_short v238, v12, s[10:11] offset:-1952
	global_store_short_d16_hi v238, v12, s[10:11] offset:2656
	global_store_short v238, v13, s[12:13] offset:-1952
	global_store_short_d16_hi v238, v13, s[12:13] offset:2656
	s_add_u32 s4, s4, 0x90000
	s_addc_u32 s5, s5, 0
	s_add_u32 s8, s4, 0x2400
	s_addc_u32 s9, s5, 0
	s_add_u32 s10, s4, 0x24000
	s_addc_u32 s11, s5, 0
	s_add_u32 s12, s10, 0x2400
	s_addc_u32 s13, s11, 0
	v_pk_mul_f32 v[152:153], v[118:119], v[194:195]
	v_pk_mul_f32 v[154:155], v[120:121], v[196:197]
	v_pk_mul_f32 v[118:119], v[118:119], v[190:191]
	v_pk_mul_f32 v[120:121], v[120:121], v[192:193]
	v_pk_fma_f32 v[152:153], v[114:115], v[190:191], v[152:153] neg_lo:[0,0,1] neg_hi:[0,0,1]
	v_pk_fma_f32 v[154:155], v[116:117], v[192:193], v[154:155] neg_lo:[0,0,1] neg_hi:[0,0,1]
	v_pk_fma_f32 v[118:119], v[114:115], v[194:195], v[118:119]
	v_pk_fma_f32 v[120:121], v[116:117], v[196:197], v[120:121]
	v_pk_mul_f32 v[152:153], v[152:153], s[84:85] op_sel_hi:[1,0]
	v_pk_mul_f32 v[154:155], v[154:155], s[84:85] op_sel_hi:[1,0]
	v_pk_mul_f32 v[118:119], v[118:119], s[84:85] op_sel_hi:[1,0]
	v_pk_mul_f32 v[120:121], v[120:121], s[84:85] op_sel_hi:[1,0]
	v_cvt_pk_bf16_f32 v114, v152, v153
	v_cvt_pk_bf16_f32 v115, v154, v155
	v_cvt_pk_bf16_f32 v116, v118, v119
	v_cvt_pk_bf16_f32 v117, v120, v121
	global_store_dwordx2 v189, v[114:115], s[78:79] offset:256
	global_store_dwordx2 v189, v[116:117], s[78:79] offset:320
	global_store_short v238, v114, s[4:5] offset:-2304
	global_store_short_d16_hi v238, v114, s[4:5] offset:2304
	global_store_short v238, v115, s[8:9] offset:-2304
	global_store_short_d16_hi v238, v115, s[8:9] offset:2304
	global_store_short v238, v116, s[10:11] offset:-2304
	global_store_short_d16_hi v238, v116, s[10:11] offset:2304
	global_store_short v238, v117, s[12:13] offset:-2304
	global_store_short_d16_hi v238, v117, s[12:13] offset:2304
	v_pk_mul_f32 v[156:157], v[102:103], v[202:203]
	v_pk_mul_f32 v[168:169], v[104:105], v[204:205]
	v_pk_mul_f32 v[102:103], v[102:103], v[198:199]
	v_pk_mul_f32 v[104:105], v[104:105], v[200:201]
	v_pk_fma_f32 v[156:157], v[98:99], v[198:199], v[156:157] neg_lo:[0,0,1] neg_hi:[0,0,1]
	v_pk_fma_f32 v[168:169], v[100:101], v[200:201], v[168:169] neg_lo:[0,0,1] neg_hi:[0,0,1]
	v_pk_fma_f32 v[102:103], v[98:99], v[202:203], v[102:103]
	v_pk_fma_f32 v[104:105], v[100:101], v[204:205], v[104:105]
	v_pk_mul_f32 v[156:157], v[156:157], s[84:85] op_sel_hi:[1,0]
	v_pk_mul_f32 v[168:169], v[168:169], s[84:85] op_sel_hi:[1,0]
	v_pk_mul_f32 v[102:103], v[102:103], s[84:85] op_sel_hi:[1,0]
	v_pk_mul_f32 v[104:105], v[104:105], s[84:85] op_sel_hi:[1,0]
	v_cvt_pk_bf16_f32 v98, v156, v157
	v_cvt_pk_bf16_f32 v99, v168, v169
	v_cvt_pk_bf16_f32 v100, v102, v103
	v_cvt_pk_bf16_f32 v101, v104, v105
	v_add_u32_e32 v239, 0x4000, v189
	global_store_dwordx2 v239, v[98:99], s[78:79] offset:256
	global_store_dwordx2 v239, v[100:101], s[78:79] offset:320
	global_store_short v238, v98, s[4:5] offset:-2272
	global_store_short_d16_hi v238, v98, s[4:5] offset:2336
	global_store_short v238, v99, s[8:9] offset:-2272
	global_store_short_d16_hi v238, v99, s[8:9] offset:2336
	global_store_short v238, v100, s[10:11] offset:-2272
	global_store_short_d16_hi v238, v100, s[10:11] offset:2336
	global_store_short v238, v101, s[12:13] offset:-2272
	global_store_short_d16_hi v238, v101, s[12:13] offset:2336
	v_pk_mul_f32 v[152:153], v[86:87], v[210:211]
	v_pk_mul_f32 v[154:155], v[88:89], v[212:213]
	v_pk_mul_f32 v[86:87], v[86:87], v[206:207]
	v_pk_mul_f32 v[88:89], v[88:89], v[208:209]
	v_pk_fma_f32 v[152:153], v[82:83], v[206:207], v[152:153] neg_lo:[0,0,1] neg_hi:[0,0,1]
	v_pk_fma_f32 v[154:155], v[84:85], v[208:209], v[154:155] neg_lo:[0,0,1] neg_hi:[0,0,1]
	v_pk_fma_f32 v[86:87], v[82:83], v[210:211], v[86:87]
	v_pk_fma_f32 v[88:89], v[84:85], v[212:213], v[88:89]
	v_pk_mul_f32 v[152:153], v[152:153], s[84:85] op_sel_hi:[1,0]
	v_pk_mul_f32 v[154:155], v[154:155], s[84:85] op_sel_hi:[1,0]
	v_pk_mul_f32 v[86:87], v[86:87], s[84:85] op_sel_hi:[1,0]
	v_pk_mul_f32 v[88:89], v[88:89], s[84:85] op_sel_hi:[1,0]
	v_cvt_pk_bf16_f32 v82, v152, v153
	v_cvt_pk_bf16_f32 v83, v154, v155
	v_cvt_pk_bf16_f32 v84, v86, v87
	v_cvt_pk_bf16_f32 v85, v88, v89
	v_add_u32_e32 v239, 0x8000, v189
	global_store_dwordx2 v239, v[82:83], s[78:79] offset:256
	global_store_dwordx2 v239, v[84:85], s[78:79] offset:320
	global_store_short v238, v82, s[4:5] offset:-2240
	global_store_short_d16_hi v238, v82, s[4:5] offset:2368
	global_store_short v238, v83, s[8:9] offset:-2240
	global_store_short_d16_hi v238, v83, s[8:9] offset:2368
	global_store_short v238, v84, s[10:11] offset:-2240
	global_store_short_d16_hi v238, v84, s[10:11] offset:2368
	global_store_short v238, v85, s[12:13] offset:-2240
	global_store_short_d16_hi v238, v85, s[12:13] offset:2368
	v_pk_mul_f32 v[156:157], v[70:71], v[218:219]
	v_pk_mul_f32 v[168:169], v[72:73], v[220:221]
	v_pk_mul_f32 v[70:71], v[70:71], v[214:215]
	v_pk_mul_f32 v[72:73], v[72:73], v[216:217]
	v_pk_fma_f32 v[156:157], v[66:67], v[214:215], v[156:157] neg_lo:[0,0,1] neg_hi:[0,0,1]
	v_pk_fma_f32 v[168:169], v[68:69], v[216:217], v[168:169] neg_lo:[0,0,1] neg_hi:[0,0,1]
	v_pk_fma_f32 v[70:71], v[66:67], v[218:219], v[70:71]
; __device__ __forceinline__ unsigned pk2(float lo, float hi) { const f32x2_t v = {lo, hi}; const bf16v2_t b = __builtin_convertvector(v, bf16v2_t); return __builtin_bit_cast(unsigned, b); }
;     __device__ __forceinline__ void operator()(const AccT& acc, const pg8::Unit& u, int wr, int wc, int fr_, int fq_) const {
;     ...
;                         const int hq = 4 * (pn & 1) + 2 * bj + (wc >> 1);
;                         const f32x4 a1 = acc[ai][bj][m][0], a2 = acc[ai][bj][m][1];
;                         f32x4 o1 = a1 * cs - a2 * sn, o2 = a1 * sn + a2 * cs;
;                         if (isk) { o1 *= 0.125f; o2 *= 0.125f; }
;                         u32x2 p1, p2; p1.x = pk2(o1[0], o1[1]); p1.y = pk2(o1[2], o1[3]); p2.x = pk2(o2[0], o2[1]); p2.y = pk2(o2[2], o2[3]);
;                         bf16_t* dst = (isk ? KN : Q) + row * 512 + hq * 64 + jj0;
;                         *(u32x2*)dst = p1; *(u32x2*)(dst + 32) = p2;
;                         if (isk) {
;                             bf16_t* kt = KT + ((size_t)(b * NH + hq) * DK + jj0) * TB + pt * 256 + rl;
;                             kt[0] = (bf16_t)(p1.x & 0xffffu); kt[(size_t)TB] = (bf16_t)(p1.x >> 16); kt[(size_t)2 * TB] = (bf16_t)(p1.y & 0xffffu); kt[(size_t)3 * TB] = (bf16_t)(p1.y >> 16);
;                             bf16_t* kt2 = kt + (size_t)32 * TB;
;                             kt2[0] = (bf16_t)(p2.x & 0xffffu); kt2[(size_t)TB] = (bf16_t)(p2.x >> 16); kt2[(size_t)2 * TB] = (bf16_t)(p2.y & 0xffffu); kt2[(size_t)3 * TB] = (bf16_t)(p2.y >> 16);
;                         }
	v_pk_fma_f32 v[72:73], v[68:69], v[220:221], v[72:73]
	v_pk_mul_f32 v[156:157], v[156:157], s[84:85] op_sel_hi:[1,0]
	v_pk_mul_f32 v[168:169], v[168:169], s[84:85] op_sel_hi:[1,0]
	v_pk_mul_f32 v[70:71], v[70:71], s[84:85] op_sel_hi:[1,0]
	v_pk_mul_f32 v[72:73], v[72:73], s[84:85] op_sel_hi:[1,0]
	v_cvt_pk_bf16_f32 v66, v156, v157
	v_cvt_pk_bf16_f32 v67, v168, v169
	v_cvt_pk_bf16_f32 v68, v70, v71
	v_cvt_pk_bf16_f32 v69, v72, v73
	v_add_u32_e32 v239, 0xc000, v189
	global_store_dwordx2 v239, v[66:67], s[78:79] offset:256
	global_store_dwordx2 v239, v[68:69], s[78:79] offset:320
	global_store_short v238, v66, s[4:5] offset:-2208
	global_store_short_d16_hi v238, v66, s[4:5] offset:2400
	global_store_short v238, v67, s[8:9] offset:-2208
	global_store_short_d16_hi v238, v67, s[8:9] offset:2400
	global_store_short v238, v68, s[10:11] offset:-2208
	global_store_short_d16_hi v238, v68, s[10:11] offset:2400
	global_store_short v238, v69, s[12:13] offset:-2208
	global_store_short_d16_hi v238, v69, s[12:13] offset:2400
	v_pk_mul_f32 v[152:153], v[54:55], v[226:227]
	v_pk_mul_f32 v[154:155], v[56:57], v[228:229]
	v_pk_mul_f32 v[54:55], v[54:55], v[222:223]
	v_pk_mul_f32 v[56:57], v[56:57], v[224:225]
	v_pk_fma_f32 v[152:153], v[50:51], v[222:223], v[152:153] neg_lo:[0,0,1] neg_hi:[0,0,1]
	v_pk_fma_f32 v[154:155], v[52:53], v[224:225], v[154:155] neg_lo:[0,0,1] neg_hi:[0,0,1]
	v_pk_fma_f32 v[54:55], v[50:51], v[226:227], v[54:55]
	v_pk_fma_f32 v[56:57], v[52:53], v[228:229], v[56:57]
	v_pk_mul_f32 v[152:153], v[152:153], s[84:85] op_sel_hi:[1,0]
	v_pk_mul_f32 v[154:155], v[154:155], s[84:85] op_sel_hi:[1,0]
	v_pk_mul_f32 v[54:55], v[54:55], s[84:85] op_sel_hi:[1,0]
	v_pk_mul_f32 v[56:57], v[56:57], s[84:85] op_sel_hi:[1,0]
	v_cvt_pk_bf16_f32 v50, v152, v153
	v_cvt_pk_bf16_f32 v51, v154, v155
	v_cvt_pk_bf16_f32 v52, v54, v55
	v_cvt_pk_bf16_f32 v53, v56, v57
	v_add_u32_e32 v239, 0x20000, v189
	global_store_dwordx2 v239, v[50:51], s[78:79] offset:256
	global_store_dwordx2 v239, v[52:53], s[78:79] offset:320
	global_store_short v238, v50, s[4:5] offset:-2048
	global_store_short_d16_hi v238, v50, s[4:5] offset:2560
	global_store_short v238, v51, s[8:9] offset:-2048
	global_store_short_d16_hi v238, v51, s[8:9] offset:2560
	global_store_short v238, v52, s[10:11] offset:-2048
	global_store_short_d16_hi v238, v52, s[10:11] offset:2560
	global_store_short v238, v53, s[12:13] offset:-2048
	global_store_short_d16_hi v238, v53, s[12:13] offset:2560
	v_pk_mul_f32 v[156:157], v[38:39], v[234:235]
	v_pk_mul_f32 v[168:169], v[40:41], v[236:237]
	v_pk_mul_f32 v[38:39], v[38:39], v[230:231]
	v_pk_mul_f32 v[40:41], v[40:41], v[232:233]
	v_pk_fma_f32 v[156:157], v[34:35], v[230:231], v[156:157] neg_lo:[0,0,1] neg_hi:[0,0,1]
	v_pk_fma_f32 v[168:169], v[36:37], v[232:233], v[168:169] neg_lo:[0,0,1] neg_hi:[0,0,1]
	v_pk_fma_f32 v[38:39], v[34:35], v[234:235], v[38:39]
	v_pk_fma_f32 v[40:41], v[36:37], v[236:237], v[40:41]
	v_pk_mul_f32 v[156:157], v[156:157], s[84:85] op_sel_hi:[1,0]
	v_pk_mul_f32 v[168:169], v[168:169], s[84:85] op_sel_hi:[1,0]
	v_pk_mul_f32 v[38:39], v[38:39], s[84:85] op_sel_hi:[1,0]
	v_pk_mul_f32 v[40:41], v[40:41], s[84:85] op_sel_hi:[1,0]
	v_cvt_pk_bf16_f32 v34, v156, v157
	v_cvt_pk_bf16_f32 v35, v168, v169
	v_cvt_pk_bf16_f32 v36, v38, v39
	v_cvt_pk_bf16_f32 v37, v40, v41
	v_add_u32_e32 v239, 0x24000, v189
	global_store_dwordx2 v239, v[34:35], s[78:79] offset:256
	global_store_dwordx2 v239, v[36:37], s[78:79] offset:320
	global_store_short v238, v34, s[4:5] offset:-2016
	global_store_short_d16_hi v238, v34, s[4:5] offset:2592
	global_store_short v238, v35, s[8:9] offset:-2016
	global_store_short_d16_hi v238, v35, s[8:9] offset:2592
	global_store_short v238, v36, s[10:11] offset:-2016
	global_store_short_d16_hi v238, v36, s[10:11] offset:2592
	global_store_short v238, v37, s[12:13] offset:-2016
	global_store_short_d16_hi v238, v37, s[12:13] offset:2592
	v_pk_mul_f32 v[152:153], v[22:23], v[134:135]
	v_pk_mul_f32 v[154:155], v[24:25], v[136:137]
	v_pk_mul_f32 v[22:23], v[22:23], v[130:131]
	v_pk_mul_f32 v[24:25], v[24:25], v[132:133]
	v_pk_fma_f32 v[152:153], v[18:19], v[130:131], v[152:153] neg_lo:[0,0,1] neg_hi:[0,0,1]
	v_pk_fma_f32 v[154:155], v[20:21], v[132:133], v[154:155] neg_lo:[0,0,1] neg_hi:[0,0,1]
	v_pk_fma_f32 v[22:23], v[18:19], v[134:135], v[22:23]
	v_pk_fma_f32 v[24:25], v[20:21], v[136:137], v[24:25]
	v_pk_mul_f32 v[152:153], v[152:153], s[84:85] op_sel_hi:[1,0]
	v_pk_mul_f32 v[154:155], v[154:155], s[84:85] op_sel_hi:[1,0]
	v_pk_mul_f32 v[22:23], v[22:23], s[84:85] op_sel_hi:[1,0]
	v_pk_mul_f32 v[24:25], v[24:25], s[84:85] op_sel_hi:[1,0]
	v_cvt_pk_bf16_f32 v18, v152, v153
	v_cvt_pk_bf16_f32 v19, v154, v155
	v_cvt_pk_bf16_f32 v20, v22, v23
	v_cvt_pk_bf16_f32 v21, v24, v25
	v_add_u32_e32 v239, 0x28000, v189
	global_store_dwordx2 v239, v[18:19], s[78:79] offset:256
	global_store_dwordx2 v239, v[20:21], s[78:79] offset:320
	global_store_short v238, v18, s[4:5] offset:-1984
	global_store_short_d16_hi v238, v18, s[4:5] offset:2624
	global_store_short v238, v19, s[8:9] offset:-1984
	global_store_short_d16_hi v238, v19, s[8:9] offset:2624
	global_store_short v238, v20, s[10:11] offset:-1984
	global_store_short_d16_hi v238, v20, s[10:11] offset:2624
	global_store_short v238, v21, s[12:13] offset:-1984
	global_store_short_d16_hi v238, v21, s[12:13] offset:2624
	v_pk_mul_f32 v[156:157], v[2:3], v[162:163]
	v_pk_mul_f32 v[168:169], v[4:5], v[164:165]
	v_pk_mul_f32 v[2:3], v[2:3], v[158:159]
	v_pk_mul_f32 v[4:5], v[4:5], v[160:161]
	v_pk_fma_f32 v[156:157], v[6:7], v[158:159], v[156:157] neg_lo:[0,0,1] neg_hi:[0,0,1]
	v_pk_fma_f32 v[168:169], v[8:9], v[160:161], v[168:169] neg_lo:[0,0,1] neg_hi:[0,0,1]
	v_pk_fma_f32 v[2:3], v[6:7], v[162:163], v[2:3]
	v_pk_fma_f32 v[4:5], v[8:9], v[164:165], v[4:5]
	v_pk_mul_f32 v[156:157], v[156:157], s[84:85] op_sel_hi:[1,0]
	v_pk_mul_f32 v[168:169], v[168:169], s[84:85] op_sel_hi:[1,0]
	v_pk_mul_f32 v[2:3], v[2:3], s[84:85] op_sel_hi:[1,0]
	v_pk_mul_f32 v[4:5], v[4:5], s[84:85] op_sel_hi:[1,0]
	v_cvt_pk_bf16_f32 v6, v156, v157
	v_cvt_pk_bf16_f32 v7, v168, v169
	v_cvt_pk_bf16_f32 v8, v2, v3
	v_cvt_pk_bf16_f32 v9, v4, v5
	v_add_u32_e32 v239, 0x2c000, v189
	global_store_dwordx2 v239, v[6:7], s[78:79] offset:256
	global_store_dwordx2 v239, v[8:9], s[78:79] offset:320
	global_store_short v238, v6, s[4:5] offset:-1952
	global_store_short_d16_hi v238, v6, s[4:5] offset:2656
	global_store_short v238, v7, s[8:9] offset:-1952
	global_store_short_d16_hi v238, v7, s[8:9] offset:2656
	global_store_short v238, v8, s[10:11] offset:-1952
	global_store_short_d16_hi v238, v8, s[10:11] offset:2656
	global_store_short v238, v9, s[12:13] offset:-1952
	global_store_short_d16_hi v238, v9, s[12:13] offset:2656
	s_branch .LBB0_323
; template <class Epi>
; __device__ __forceinline__ void gemm_phase(LAS unsigned char* lds, const Gemm g, const Epi& E) {
;     ...
; #pragma unroll
;         for (int a = 0; a < 2; ++a)
; #pragma unroll
;             for (int b = 0; b < 2; ++b)
; #pragma unroll
;                 for (int m = 0; m < 4; ++m)
; #pragma unroll
;                     for (int n = 0; n < 2; ++n) acc[a][b][m][n] = (f32x4){0.f, 0.f, 0.f, 0.f};
.LBB0_268:
	v_mov_b32_e32 v125, 0
	v_mov_b32_e32 v124, v125
	v_mov_b32_e32 v123, v125
	v_mov_b32_e32 v122, v125
	v_mov_b32_e32 v129, v125
	v_mov_b32_e32 v128, v125
	v_mov_b32_e32 v127, v125
	v_mov_b32_e32 v126, v125
	v_mov_b32_e32 v109, v125
	v_mov_b32_e32 v108, v125
	v_mov_b32_e32 v107, v125
	v_mov_b32_e32 v106, v125
	v_mov_b32_e32 v113, v125
	v_mov_b32_e32 v112, v125
	v_mov_b32_e32 v111, v125
	v_mov_b32_e32 v110, v125
	v_mov_b32_e32 v93, v125
	v_mov_b32_e32 v92, v125
	v_mov_b32_e32 v91, v125
	v_mov_b32_e32 v90, v125
	v_mov_b32_e32 v97, v125
	v_mov_b32_e32 v96, v125
	v_mov_b32_e32 v95, v125
	v_mov_b32_e32 v94, v125
	v_mov_b32_e32 v77, v125
	v_mov_b32_e32 v76, v125
	v_mov_b32_e32 v75, v125
	v_mov_b32_e32 v74, v125
	v_mov_b32_e32 v81, v125
	v_mov_b32_e32 v80, v125
	v_mov_b32_e32 v79, v125
	v_mov_b32_e32 v78, v125
	v_mov_b32_e32 v117, v125
	v_mov_b32_e32 v116, v125
	v_mov_b32_e32 v115, v125
	v_mov_b32_e32 v114, v125
	v_mov_b32_e32 v121, v125
	v_mov_b32_e32 v120, v125
	v_mov_b32_e32 v119, v125
	v_mov_b32_e32 v118, v125
	v_mov_b32_e32 v101, v125
	v_mov_b32_e32 v100, v125
	v_mov_b32_e32 v99, v125
	v_mov_b32_e32 v98, v125
	v_mov_b32_e32 v105, v125
	v_mov_b32_e32 v104, v125
	v_mov_b32_e32 v103, v125
	v_mov_b32_e32 v102, v125
	v_mov_b32_e32 v85, v125
	v_mov_b32_e32 v84, v125
	v_mov_b32_e32 v83, v125
	v_mov_b32_e32 v82, v125
	v_mov_b32_e32 v89, v125
	v_mov_b32_e32 v88, v125
	v_mov_b32_e32 v87, v125
	v_mov_b32_e32 v86, v125
	v_mov_b32_e32 v69, v125
	v_mov_b32_e32 v68, v125
	v_mov_b32_e32 v67, v125
	v_mov_b32_e32 v66, v125
	v_mov_b32_e32 v73, v125
	v_mov_b32_e32 v72, v125
	v_mov_b32_e32 v71, v125
	v_mov_b32_e32 v70, v125
	v_mov_b32_e32 v61, v125
	v_mov_b32_e32 v60, v125
	v_mov_b32_e32 v59, v125
	v_mov_b32_e32 v58, v125
	v_mov_b32_e32 v65, v125
	v_mov_b32_e32 v64, v125
	v_mov_b32_e32 v63, v125
	v_mov_b32_e32 v62, v125
	v_mov_b32_e32 v45, v125
	v_mov_b32_e32 v44, v125
	v_mov_b32_e32 v43, v125
	v_mov_b32_e32 v42, v125
	v_mov_b32_e32 v49, v125
	v_mov_b32_e32 v48, v125
	v_mov_b32_e32 v47, v125
	v_mov_b32_e32 v46, v125
	v_mov_b32_e32 v29, v125
	v_mov_b32_e32 v28, v125
	v_mov_b32_e32 v27, v125
	v_mov_b32_e32 v26, v125
	v_mov_b32_e32 v33, v125
	v_mov_b32_e32 v32, v125
	v_mov_b32_e32 v31, v125
	v_mov_b32_e32 v30, v125
	v_mov_b32_e32 v13, v125
	v_mov_b32_e32 v12, v125
	v_mov_b32_e32 v11, v125
	v_mov_b32_e32 v10, v125
	v_mov_b32_e32 v17, v125
	v_mov_b32_e32 v16, v125
	v_mov_b32_e32 v15, v125
	v_mov_b32_e32 v14, v125
	v_mov_b32_e32 v53, v125
	v_mov_b32_e32 v52, v125
	v_mov_b32_e32 v51, v125
	v_mov_b32_e32 v50, v125
	v_mov_b32_e32 v57, v125
	v_mov_b32_e32 v56, v125
	v_mov_b32_e32 v55, v125
	v_mov_b32_e32 v54, v125
	v_mov_b32_e32 v37, v125
	v_mov_b32_e32 v36, v125
	v_mov_b32_e32 v35, v125
	v_mov_b32_e32 v34, v125
	v_mov_b32_e32 v41, v125
	v_mov_b32_e32 v40, v125
	v_mov_b32_e32 v39, v125
	v_mov_b32_e32 v38, v125
	v_mov_b32_e32 v21, v125
	v_mov_b32_e32 v20, v125
	v_mov_b32_e32 v19, v125
	v_mov_b32_e32 v18, v125
	v_mov_b32_e32 v25, v125
	v_mov_b32_e32 v24, v125
	v_mov_b32_e32 v23, v125
	v_mov_b32_e32 v22, v125
	v_mov_b32_e32 v9, v125
	v_mov_b32_e32 v8, v125
	v_mov_b32_e32 v7, v125
	v_mov_b32_e32 v6, v125
	v_mov_b32_e32 v5, v125
	v_mov_b32_e32 v4, v125
	v_mov_b32_e32 v3, v125
	v_mov_b32_e32 v2, v125
	s_and_b64 vcc, exec, s[66:67]
	s_cbranch_vccnz .LBB0_97
	s_branch .LBB0_98
.LBB0_323:
	s_andn2_b64 vcc, exec, s[6:7]
	s_mov_b64 s[4:5], -1
	s_cbranch_vccnz .LBB0_90
